# two more norm-phase butterfly steps on DPP (wider match window)
# speedup vs baseline: 1.0068x; 1.0068x over previous
; __device__ __forceinline__ unsigned cvt_pk_bf16(float lo, float hi) { unsigned r; asm volatile("v_cvt_pk_bf16_f32 %0, %1, %2" : "=v"(r) : "v"(lo), "v"(hi)); return r; }
; __device__ __forceinline__ float wave_sum(float v) {
; #pragma unroll
;     for (int o = 1; o < 64; o <<= 1) v += __shfl_xor(v, o);
;     return v;
; }
; __device__ __forceinline__ void phase_norm(CArgs& a, int l, int which) {
;     ...
;         for (int u = 0; u < 2; ++u) { float ss = 0.f;
; #pragma unroll
;             for (int j = 0; j < 8; ++j) ss += (x[u][j].x * x[u][j].x + x[u][j].y * x[u][j].y) + (x[u][j].z * x[u][j].z + x[u][j].w * x[u][j].w);
;             const float rs = rsqrtf(wave_sum(ss) * (1.f / DM) + EPS);
;             if (!ok[u]) continue;
;             bf16_t* o = H + (size_t)(r0 + u * NGW) * DM;
; #pragma unroll
;             for (int j = 0; j < 8; ++j) { const int c = 4 * lane + 256 * j; const f32x4 g = *(const f32x4*)(gn + c), s1 = *(const f32x4*)(sc[u] + c), s0 = *(const f32x4*)(sh[u] + c);
;                 const f32x4 y = (x[u][j] * rs) * g * (1.f + s1) + s0;
;                 u32x2 w; w.x = cvt_pk_bf16(y.x, y.y); w.y = cvt_pk_bf16(y.z, y.w); *(u32x2*)(o + c) = w; } }
.LBB0_337:
	s_or_b64 exec, exec, s[20:21]
	v_cndmask_b32_e64 v99, v110, 4, s[40:41]
	s_waitcnt vmcnt(0)
	v_mul_f32_e32 v110, v63, v63
	v_mul_f32_e32 v111, v65, v65
	v_fmac_f32_e32 v110, v62, v62
	v_fmac_f32_e32 v111, v64, v64
	v_add_f32_e32 v110, v110, v111
	v_mul_f32_e32 v111, v59, v59
	v_mul_f32_e32 v113, v61, v61
	v_fmac_f32_e32 v111, v58, v58
	v_fmac_f32_e32 v113, v60, v60
	v_add_f32_e32 v111, v111, v113
	v_add_f32_e32 v110, v111, v110
	v_mul_f32_e32 v111, v51, v51
	v_mul_f32_e32 v113, v53, v53
	v_fmac_f32_e32 v111, v50, v50
	v_fmac_f32_e32 v113, v52, v52
	v_add_f32_e32 v111, v111, v113
	v_add_f32_e32 v110, v111, v110
	v_mul_f32_e32 v111, v43, v43
	v_mul_f32_e32 v113, v45, v45
	v_fmac_f32_e32 v111, v42, v42
	v_fmac_f32_e32 v113, v44, v44
	v_add_f32_e32 v111, v111, v113
	v_add_f32_e32 v110, v111, v110
	v_mul_f32_e32 v111, v35, v35
	v_mul_f32_e32 v113, v37, v37
	v_fmac_f32_e32 v111, v34, v34
	v_fmac_f32_e32 v113, v36, v36
	v_add_f32_e32 v111, v111, v113
	v_add_f32_e32 v110, v111, v110
	v_mul_f32_e32 v111, v27, v27
	v_mul_f32_e32 v113, v29, v29
	v_fmac_f32_e32 v111, v26, v26
	v_fmac_f32_e32 v113, v28, v28
	v_add_f32_e32 v111, v111, v113
	v_add_f32_e32 v110, v111, v110
	v_mul_f32_e32 v111, v19, v19
	v_mul_f32_e32 v113, v21, v21
	v_fmac_f32_e32 v111, v18, v18
	v_fmac_f32_e32 v113, v20, v20
	v_add_f32_e32 v111, v111, v113
	v_add_f32_e32 v110, v111, v110
	v_mul_f32_e32 v111, v11, v11
	v_mul_f32_e32 v113, v13, v13
	v_fmac_f32_e32 v111, v10, v10
	v_fmac_f32_e32 v113, v12, v12
	v_add_f32_e32 v111, v111, v113
	v_add_f32_e32 v110, v111, v110
	s_nop 1
	s_and_b64 s[4:5], s[46:47], s[42:43]
	s_xor_b64 s[4:5], s[4:5], -1
	v_lshlrev_b32_e32 v124, 2, v84
	v_lshlrev_b32_e32 v122, 2, v86
	v_add_f32_dpp v110, v110, v110 quad_perm:[1,0,3,2] row_mask:0xf bank_mask:0xf
	s_nop 1
	v_lshlrev_b32_e32 v120, 2, v88
	v_lshlrev_b32_e32 v118, 2, v90
	v_lshlrev_b32_e32 v116, 2, v94
	v_lshlrev_b32_e32 v114, 2, v98
	v_add_f32_dpp v110, v110, v110 quad_perm:[2,3,0,1] row_mask:0xf bank_mask:0xf
	s_nop 1
	v_add_f32_dpp v110, v110, v110 row_half_mirror row_mask:0xf bank_mask:0xf
	s_nop 1
	v_add_f32_dpp v110, v110, v110 row_mirror row_mask:0xf bank_mask:0xf
	v_mov_b32_e32 v111, v110
	s_nop 1
	v_permlane16_swap_b32_e32 v110, v111
	v_add_f32_e32 v111, v110, v111
	ds_bpermute_b32 v113, v95, v111
	v_lshlrev_b32_e32 v110, 2, v102
	s_and_saveexec_b64 s[20:21], s[4:5]
	s_cbranch_execz .LBB0_339
	v_mul_hi_i32_i24_e32 v127, 0xc000, v103
	v_mul_i32_i24_e32 v126, 0xc000, v103
	v_lshl_add_u64 v[126:127], s[72:73], 0, v[126:127]
	v_lshl_add_u64 v[128:129], v[126:127], 0, s[96:97]
	v_lshl_add_u64 v[132:133], v[128:129], 0, v[0:1]
	global_load_dwordx4 v[134:137], v[82:83], off
	global_load_dwordx4 v[138:141], v[132:133], off
	v_lshl_add_u64 v[132:133], v[126:127], 0, v[0:1]
	global_load_dwordx4 v[142:145], v[132:133], off
	s_waitcnt lgkmcnt(0)
	v_add_f32_e32 v103, v111, v113
	v_fmamk_f32 v103, v103, 0x3a000000, v216
	v_cmp_gt_f32_e32 vcc, s26, v103
	v_mul_f32_e32 v111, 0x4b800000, v103
	v_lshlrev_b64 v[146:147], 12, v[66:67]
	v_cndmask_b32_e32 v103, v103, v111, vcc
	v_rsq_f32_e32 v103, v103
	v_mov_b32_e32 v125, v1
	v_mov_b32_e32 v123, v1
	v_mov_b32_e32 v121, v1
	v_mul_f32_e32 v111, 0x45800000, v103
	v_cndmask_b32_e32 v130, v103, v111, vcc
	v_pk_mul_f32 v[64:65], v[64:65], v[130:131] op_sel_hi:[1,0]
	v_pk_mul_f32 v[62:63], v[62:63], v[130:131] op_sel_hi:[1,0]
	v_pk_mul_f32 v[58:59], v[58:59], v[130:131] op_sel_hi:[1,0]
	v_pk_mul_f32 v[60:61], v[60:61], v[130:131] op_sel_hi:[1,0]
	v_pk_mul_f32 v[52:53], v[52:53], v[130:131] op_sel_hi:[1,0]
	v_pk_mul_f32 v[50:51], v[50:51], v[130:131] op_sel_hi:[1,0]
	v_pk_mul_f32 v[44:45], v[44:45], v[130:131] op_sel_hi:[1,0]
	v_pk_mul_f32 v[42:43], v[42:43], v[130:131] op_sel_hi:[1,0]
	v_mov_b32_e32 v119, v1
	v_pk_mul_f32 v[36:37], v[36:37], v[130:131] op_sel_hi:[1,0]
	v_pk_mul_f32 v[34:35], v[34:35], v[130:131] op_sel_hi:[1,0]
	v_mov_b32_e32 v117, v1
	v_pk_mul_f32 v[28:29], v[28:29], v[130:131] op_sel_hi:[1,0]
	v_pk_mul_f32 v[26:27], v[26:27], v[130:131] op_sel_hi:[1,0]
	v_mov_b32_e32 v115, v1
	v_pk_mul_f32 v[20:21], v[20:21], v[130:131] op_sel_hi:[1,0]
	v_pk_mul_f32 v[18:19], v[18:19], v[130:131] op_sel_hi:[1,0]
	v_mov_b32_e32 v111, v1
	v_pk_mul_f32 v[12:13], v[12:13], v[130:131] op_sel_hi:[1,0]
	v_pk_mul_f32 v[10:11], v[10:11], v[130:131] op_sel_hi:[1,0]
	s_waitcnt vmcnt(2)
	v_pk_mul_f32 v[62:63], v[62:63], v[134:135]
	v_pk_mul_f32 v[64:65], v[64:65], v[136:137]
	s_waitcnt vmcnt(1)
	v_pk_add_f32 v[136:137], v[138:139], 1.0 op_sel_hi:[1,0]
	v_pk_add_f32 v[134:135], v[140:141], 1.0 op_sel_hi:[1,0]
	s_waitcnt vmcnt(0)
	v_pk_fma_f32 v[62:63], v[62:63], v[136:137], v[142:143]
	v_pk_fma_f32 v[64:65], v[64:65], v[134:135], v[144:145]
	v_cvt_pk_bf16_f32 v134, v62, v63
	v_lshl_add_u64 v[62:63], v[106:107], 0, v[146:147]
	v_cvt_pk_bf16_f32 v135, v64, v65
	global_store_dwordx2 v[62:63], v[134:135], off
	global_load_dwordx4 v[134:137], v[82:83], off offset:1024
	v_lshl_add_u64 v[64:65], v[128:129], 0, v[124:125]
	global_load_dwordx4 v[138:141], v[64:65], off
	global_load_dwordx4 v[142:145], v[132:133], off offset:1024
	s_waitcnt vmcnt(2)
; __device__ __forceinline__ unsigned cvt_pk_bf16(float lo, float hi) { unsigned r; asm volatile("v_cvt_pk_bf16_f32 %0, %1, %2" : "=v"(r) : "v"(lo), "v"(hi)); return r; }
; __device__ __forceinline__ void phase_norm(CArgs& a, int l, int which) {
;     ...
; #pragma unroll
;             for (int j = 0; j < 8; ++j) { const int c = 4 * lane + 256 * j; const f32x4 g = *(const f32x4*)(gn + c), s1 = *(const f32x4*)(sc[u] + c), s0 = *(const f32x4*)(sh[u] + c);
;                 const f32x4 y = (x[u][j] * rs) * g * (1.f + s1) + s0;
;                 u32x2 w; w.x = cvt_pk_bf16(y.x, y.y); w.y = cvt_pk_bf16(y.z, y.w); *(u32x2*)(o + c) = w; } }
	v_pk_mul_f32 v[58:59], v[58:59], v[134:135]
	s_waitcnt vmcnt(1)
	v_pk_add_f32 v[134:135], v[138:139], 1.0 op_sel_hi:[1,0]
	v_pk_mul_f32 v[60:61], v[60:61], v[136:137]
	v_pk_add_f32 v[64:65], v[140:141], 1.0 op_sel_hi:[1,0]
	s_waitcnt vmcnt(0)
	v_pk_fma_f32 v[58:59], v[58:59], v[134:135], v[142:143]
	v_pk_fma_f32 v[60:61], v[60:61], v[64:65], v[144:145]
	v_cvt_pk_bf16_f32 v58, v58, v59
	v_lshl_add_u64 v[64:65], v[128:129], 0, v[122:123]
	v_cvt_pk_bf16_f32 v59, v60, v61
	global_store_dwordx2 v[62:63], v[58:59], off offset:512
	global_load_dwordx4 v[58:61], v[82:83], off offset:2048
	s_nop 0
	global_load_dwordx4 v[134:137], v[64:65], off
	global_load_dwordx4 v[138:141], v[132:133], off offset:2048
	s_waitcnt vmcnt(2)
	v_pk_mul_f32 v[50:51], v[50:51], v[58:59]
	v_pk_mul_f32 v[52:53], v[52:53], v[60:61]
	s_waitcnt vmcnt(1)
	v_pk_add_f32 v[60:61], v[134:135], 1.0 op_sel_hi:[1,0]
	v_pk_add_f32 v[58:59], v[136:137], 1.0 op_sel_hi:[1,0]
	s_waitcnt vmcnt(0)
	v_pk_fma_f32 v[50:51], v[50:51], v[60:61], v[138:139]
	v_pk_fma_f32 v[52:53], v[52:53], v[58:59], v[140:141]
	v_cvt_pk_bf16_f32 v50, v50, v51
	v_lshl_add_u64 v[58:59], v[128:129], 0, v[120:121]
	v_cvt_pk_bf16_f32 v51, v52, v53
	global_store_dwordx2 v[62:63], v[50:51], off offset:1024
	global_load_dwordx4 v[50:53], v[82:83], off offset:3072
	s_nop 0
	global_load_dwordx4 v[58:61], v[58:59], off
	s_nop 0
	global_load_dwordx4 v[132:135], v[132:133], off offset:3072
	s_waitcnt vmcnt(2)
	v_pk_mul_f32 v[42:43], v[42:43], v[50:51]
	v_pk_mul_f32 v[44:45], v[44:45], v[52:53]
	s_waitcnt vmcnt(1)
	v_pk_add_f32 v[52:53], v[58:59], 1.0 op_sel_hi:[1,0]
	v_pk_add_f32 v[50:51], v[60:61], 1.0 op_sel_hi:[1,0]
	s_waitcnt vmcnt(0)
	v_pk_fma_f32 v[42:43], v[42:43], v[52:53], v[132:133]
	v_pk_fma_f32 v[44:45], v[44:45], v[50:51], v[134:135]
	v_cvt_pk_bf16_f32 v42, v42, v43
	v_lshl_add_u64 v[50:51], v[128:129], 0, v[118:119]
	v_cvt_pk_bf16_f32 v43, v44, v45
	global_store_dwordx2 v[62:63], v[42:43], off offset:1536
	global_load_dwordx4 v[42:45], v[92:93], off
	v_lshl_add_u64 v[58:59], v[126:127], 0, v[118:119]
	global_load_dwordx4 v[50:53], v[50:51], off
	s_waitcnt vmcnt(1)
	v_pk_mul_f32 v[34:35], v[34:35], v[42:43]
	global_load_dwordx4 v[58:61], v[58:59], off
	v_pk_mul_f32 v[36:37], v[36:37], v[44:45]
	s_waitcnt vmcnt(1)
	v_pk_add_f32 v[44:45], v[50:51], 1.0 op_sel_hi:[1,0]
	v_pk_add_f32 v[42:43], v[52:53], 1.0 op_sel_hi:[1,0]
	v_lshl_add_u64 v[50:51], v[126:127], 0, v[116:117]
	s_waitcnt vmcnt(0)
	v_pk_fma_f32 v[34:35], v[34:35], v[44:45], v[58:59]
	v_pk_fma_f32 v[36:37], v[36:37], v[42:43], v[60:61]
	v_cvt_pk_bf16_f32 v34, v34, v35
	v_lshl_add_u64 v[42:43], v[128:129], 0, v[116:117]
	v_cvt_pk_bf16_f32 v35, v36, v37
	global_store_dwordx2 v[62:63], v[34:35], off offset:2048
	global_load_dwordx4 v[34:37], v[96:97], off
	s_waitcnt vmcnt(0)
	v_pk_mul_f32 v[26:27], v[26:27], v[34:35]
	global_load_dwordx4 v[42:45], v[42:43], off
	v_pk_mul_f32 v[28:29], v[28:29], v[36:37]
	global_load_dwordx4 v[50:53], v[50:51], off
	s_waitcnt vmcnt(1)
	v_pk_add_f32 v[36:37], v[42:43], 1.0 op_sel_hi:[1,0]
	v_pk_add_f32 v[34:35], v[44:45], 1.0 op_sel_hi:[1,0]
	s_waitcnt vmcnt(0)
	v_pk_fma_f32 v[26:27], v[26:27], v[36:37], v[50:51]
	v_pk_fma_f32 v[28:29], v[28:29], v[34:35], v[52:53]
	v_cvt_pk_bf16_f32 v26, v26, v27
	v_lshl_add_u64 v[34:35], v[128:129], 0, v[114:115]
	v_cvt_pk_bf16_f32 v27, v28, v29
	global_store_dwordx2 v[62:63], v[26:27], off offset:2560
	global_load_dwordx4 v[26:29], v[100:101], off
	v_lshl_add_u64 v[42:43], v[126:127], 0, v[114:115]
	global_load_dwordx4 v[34:37], v[34:35], off
	s_waitcnt vmcnt(1)
	v_pk_mul_f32 v[18:19], v[18:19], v[26:27]
	global_load_dwordx4 v[42:45], v[42:43], off
	v_pk_mul_f32 v[20:21], v[20:21], v[28:29]
	s_waitcnt vmcnt(1)
	v_pk_add_f32 v[28:29], v[34:35], 1.0 op_sel_hi:[1,0]
	v_pk_add_f32 v[26:27], v[36:37], 1.0 op_sel_hi:[1,0]
	v_lshl_add_u64 v[34:35], v[126:127], 0, v[110:111]
	s_waitcnt vmcnt(0)
	v_pk_fma_f32 v[18:19], v[18:19], v[28:29], v[42:43]
	v_pk_fma_f32 v[20:21], v[20:21], v[26:27], v[44:45]
	v_cvt_pk_bf16_f32 v18, v18, v19
	v_lshl_add_u64 v[26:27], v[128:129], 0, v[110:111]
	v_cvt_pk_bf16_f32 v19, v20, v21
	global_store_dwordx2 v[62:63], v[18:19], off offset:3072
	global_load_dwordx4 v[18:21], v[104:105], off
	s_waitcnt vmcnt(0)
	v_pk_mul_f32 v[10:11], v[10:11], v[18:19]
	global_load_dwordx4 v[26:29], v[26:27], off
	v_pk_mul_f32 v[12:13], v[12:13], v[20:21]
	global_load_dwordx4 v[34:37], v[34:35], off
	s_waitcnt vmcnt(1)
	v_pk_add_f32 v[20:21], v[26:27], 1.0 op_sel_hi:[1,0]
	v_pk_add_f32 v[18:19], v[28:29], 1.0 op_sel_hi:[1,0]
	s_waitcnt vmcnt(0)
	v_pk_fma_f32 v[10:11], v[10:11], v[20:21], v[34:35]
	v_pk_fma_f32 v[12:13], v[12:13], v[18:19], v[36:37]
	v_cvt_pk_bf16_f32 v10, v10, v11
	s_nop 0
	v_cvt_pk_bf16_f32 v11, v12, v13
	global_store_dwordx2 v[62:63], v[10:11], off offset:3584
